# P8-unit-start-no-store-ack-wait
# speedup vs baseline: 1.0015x; 1.0015x over previous
.LBB0_779:
	s_mul_i32 s76, s75, 0x7e000
	s_and_b64 s[0:1], s[8:9], exec
	s_cselect_b32 s0, s76, s2
	s_lshl_b32 s77, s74, 19
	s_and_b64 s[12:13], s[8:9], exec
	v_mov_b32_e32 v12, 0
	s_cselect_b32 s1, s77, s3
	s_addk_i32 s2, 0x2080
	s_addk_i32 s3, 0x100
	s_mov_b32 s11, -2
	ds_read_b128 v[128:131], v207
	ds_read_b128 v[132:135], v207 offset:1024
	ds_read_b128 v[136:139], v207 offset:2048
	ds_read_b128 v[140:143], v207 offset:3072
	ds_read_b128 v[144:147], v208
	ds_read_b128 v[148:151], v208 offset:1024
	ds_read_b128 v[152:155], v208 offset:2048
	ds_read_b128 v[156:159], v208 offset:3072
	s_add_i32 s12, s2, 0xffffe080
	s_cmp_eq_u32 s11, 12
	s_cselect_b32 s14, s0, s12
	s_cselect_b32 s13, s1, s3
	s_or_b32 s12, s14, 0x80
	v_add_u32_e32 v184, s2, v206
	ds_read_b128 v[164:167], v209
	ds_read_b128 v[168:171], v209 offset:1024
	ds_read_b128 v[172:175], v209 offset:2048
	ds_read_b128 v[176:179], v209 offset:3072
	ds_read_b128 v[180:183], v209 offset:4096
	ds_read_b128 v[210:213], v209 offset:5120
	ds_read_b128 v[214:217], v209 offset:6144
	ds_read_b128 v[218:221], v209 offset:7168
	s_add_i32 m0, s27, 0xc000
	s_nop 0
	global_load_lds_dwordx4 v184, s[22:23]
	v_add_u32_e32 v184, s2, v205
	s_add_i32 m0, s27, 0xe000
	s_nop 0
	global_load_lds_dwordx4 v184, s[22:23]
	s_waitcnt vmcnt(8)
	s_waitcnt lgkmcnt(0)
	s_barrier
	s_waitcnt lgkmcnt(0)
	v_mfma_f32_16x16x32_bf16 v[120:123], v[128:131], v[164:167], 0
	v_mfma_f32_16x16x32_bf16 v[56:59], v[136:139], v[164:167], 0
	v_mfma_f32_16x16x32_bf16 v[112:115], v[128:131], v[172:175], 0
	v_mfma_f32_16x16x32_bf16 v[48:51], v[136:139], v[172:175], 0
	v_mfma_f32_16x16x32_bf16 v[104:107], v[128:131], v[180:183], 0
	v_mfma_f32_16x16x32_bf16 v[40:43], v[136:139], v[180:183], 0
	v_mfma_f32_16x16x32_bf16 v[96:99], v[128:131], v[214:217], 0
	v_mfma_f32_16x16x32_bf16 v[32:35], v[136:139], v[214:217], 0
	v_mfma_f32_16x16x32_bf16 v[120:123], v[132:135], v[168:171], v[120:123]
	v_mfma_f32_16x16x32_bf16 v[56:59], v[140:143], v[168:171], v[56:59]
	v_mfma_f32_16x16x32_bf16 v[112:115], v[132:135], v[176:179], v[112:115]
	v_mfma_f32_16x16x32_bf16 v[48:51], v[140:143], v[176:179], v[48:51]
	v_mfma_f32_16x16x32_bf16 v[104:107], v[132:135], v[210:213], v[104:107]
	v_mfma_f32_16x16x32_bf16 v[40:43], v[140:143], v[210:213], v[40:43]
	v_mfma_f32_16x16x32_bf16 v[96:99], v[132:135], v[218:221], v[96:99]
	v_mfma_f32_16x16x32_bf16 v[32:35], v[140:143], v[218:221], v[32:35]
	v_mfma_f32_16x16x32_bf16 v[124:127], v[144:147], v[164:167], 0
	v_mfma_f32_16x16x32_bf16 v[60:63], v[152:155], v[164:167], 0
	v_mfma_f32_16x16x32_bf16 v[116:119], v[144:147], v[172:175], 0
	v_mfma_f32_16x16x32_bf16 v[52:55], v[152:155], v[172:175], 0
	v_mfma_f32_16x16x32_bf16 v[108:111], v[144:147], v[180:183], 0
	v_mfma_f32_16x16x32_bf16 v[44:47], v[152:155], v[180:183], 0
	v_mfma_f32_16x16x32_bf16 v[100:103], v[144:147], v[214:217], 0
	v_mfma_f32_16x16x32_bf16 v[36:39], v[152:155], v[214:217], 0
	v_mfma_f32_16x16x32_bf16 v[124:127], v[148:151], v[168:171], v[124:127]
	v_mfma_f32_16x16x32_bf16 v[60:63], v[156:159], v[168:171], v[60:63]
	v_mfma_f32_16x16x32_bf16 v[116:119], v[148:151], v[176:179], v[116:119]
	v_mfma_f32_16x16x32_bf16 v[52:55], v[156:159], v[176:179], v[52:55]
	v_mfma_f32_16x16x32_bf16 v[108:111], v[148:151], v[210:213], v[108:111]
	v_mfma_f32_16x16x32_bf16 v[44:47], v[156:159], v[210:213], v[44:47]
	v_mfma_f32_16x16x32_bf16 v[100:103], v[148:151], v[218:221], v[100:103]
	v_mfma_f32_16x16x32_bf16 v[36:39], v[156:159], v[218:221], v[36:39]
	s_barrier
	v_add_u32_e32 v184, s13, v192
	s_add_i32 s15, s71, s26
	ds_read_b128 v[164:167], v209 offset:16384
	ds_read_b128 v[168:171], v209 offset:17408
	ds_read_b128 v[172:175], v209 offset:18432
	ds_read_b128 v[176:179], v209 offset:19456
	ds_read_b128 v[180:183], v209 offset:20480
	ds_read_b128 v[210:213], v209 offset:21504
	ds_read_b128 v[214:217], v209 offset:22528
	ds_read_b128 v[218:221], v209 offset:23552
	s_mov_b32 m0, s15
	s_add_i32 s16, s72, s26
	global_load_lds_dwordx4 v184, s[36:37]
	v_add_u32_e32 v184, s13, v194
	s_add_i32 m0, s15, 0x2000
	s_add_i32 s15, s13, 0x40000
	global_load_lds_dwordx4 v184, s[36:37]
	v_add_u32_e32 v184, s15, v192
	s_mov_b32 m0, s16
	s_nop 0
	global_load_lds_dwordx4 v184, s[36:37]
	v_add_u32_e32 v184, s15, v194
	s_add_i32 m0, s16, 0x2000
	s_nop 0
	global_load_lds_dwordx4 v184, s[36:37]
	v_add_u32_e32 v184, s14, v191
	s_mov_b32 m0, s27
	s_nop 0
	global_load_lds_dwordx4 v184, s[22:23]
	v_add_u32_e32 v184, s14, v193
	s_mov_b32 m0, s33
	s_nop 0
	global_load_lds_dwordx4 v184, s[22:23]
	s_waitcnt vmcnt(8)
	s_waitcnt lgkmcnt(0)
	s_barrier
	s_waitcnt lgkmcnt(0)
	v_mfma_f32_16x16x32_bf16 v[88:91], v[128:131], v[164:167], 0
	v_mfma_f32_16x16x32_bf16 v[24:27], v[136:139], v[164:167], 0
	v_mfma_f32_16x16x32_bf16 v[72:75], v[128:131], v[172:175], 0
	v_mfma_f32_16x16x32_bf16 v[8:11], v[136:139], v[172:175], 0
	v_mfma_f32_16x16x32_bf16 v[68:71], v[128:131], v[180:183], 0
	v_mfma_f32_16x16x32_bf16 v[4:7], v[136:139], v[180:183], 0
	v_mfma_f32_16x16x32_bf16 v[64:67], v[128:131], v[214:217], 0
	v_mfma_f32_16x16x32_bf16 v[0:3], v[136:139], v[214:217], 0
	v_mfma_f32_16x16x32_bf16 v[88:91], v[132:135], v[168:171], v[88:91]
	v_mfma_f32_16x16x32_bf16 v[24:27], v[140:143], v[168:171], v[24:27]
	v_mfma_f32_16x16x32_bf16 v[72:75], v[132:135], v[176:179], v[72:75]
	v_mfma_f32_16x16x32_bf16 v[8:11], v[140:143], v[176:179], v[8:11]
	v_mfma_f32_16x16x32_bf16 v[68:71], v[132:135], v[210:213], v[68:71]
	v_mfma_f32_16x16x32_bf16 v[4:7], v[140:143], v[210:213], v[4:7]
	v_mfma_f32_16x16x32_bf16 v[64:67], v[132:135], v[218:221], v[64:67]
	v_mfma_f32_16x16x32_bf16 v[0:3], v[140:143], v[218:221], v[0:3]
	v_mfma_f32_16x16x32_bf16 v[92:95], v[144:147], v[164:167], 0
	v_mfma_f32_16x16x32_bf16 v[28:31], v[152:155], v[164:167], 0
	v_mfma_f32_16x16x32_bf16 v[76:79], v[144:147], v[172:175], 0
	v_mfma_f32_16x16x32_bf16 v[16:19], v[152:155], v[172:175], 0
	v_mfma_f32_16x16x32_bf16 v[84:87], v[144:147], v[180:183], 0
	v_mfma_f32_16x16x32_bf16 v[20:23], v[152:155], v[180:183], 0
	v_mfma_f32_16x16x32_bf16 v[80:83], v[144:147], v[214:217], 0
	v_mfma_f32_16x16x32_bf16 v[12:15], v[152:155], v[214:217], 0
	v_mfma_f32_16x16x32_bf16 v[92:95], v[148:151], v[168:171], v[92:95]
	v_mfma_f32_16x16x32_bf16 v[28:31], v[156:159], v[168:171], v[28:31]
	v_mfma_f32_16x16x32_bf16 v[76:79], v[148:151], v[176:179], v[76:79]
	v_mfma_f32_16x16x32_bf16 v[16:19], v[156:159], v[176:179], v[16:19]
	v_mfma_f32_16x16x32_bf16 v[84:87], v[148:151], v[210:213], v[84:87]
	v_mfma_f32_16x16x32_bf16 v[20:23], v[156:159], v[210:213], v[20:23]
	v_mfma_f32_16x16x32_bf16 v[80:83], v[148:151], v[218:221], v[80:83]
	v_mfma_f32_16x16x32_bf16 v[12:15], v[156:159], v[218:221], v[12:15]
	s_barrier
	s_add_i32 s15, 0, 0x18000
	s_add_i32 s16, 0, 0x1c000
	v_add_u32_e32 v140, s15, v195
	v_add_u32_e32 v156, s16, v195
	ds_read_b128 v[128:131], v140
	ds_read_b128 v[132:135], v140 offset:1024
	ds_read_b128 v[136:139], v140 offset:2048
	ds_read_b128 v[140:143], v140 offset:3072
	ds_read_b128 v[144:147], v156
	ds_read_b128 v[148:151], v156 offset:1024
	ds_read_b128 v[152:155], v156 offset:2048
	ds_read_b128 v[156:159], v156 offset:3072
	s_addk_i32 s14, 0x2000
	v_add_u32_e32 v184, s14, v191
	s_mov_b32 m0, s34
	ds_read_b128 v[164:167], v209 offset:32768
	ds_read_b128 v[168:171], v209 offset:33792
	ds_read_b128 v[172:175], v209 offset:34816
	ds_read_b128 v[176:179], v209 offset:35840
	ds_read_b128 v[180:183], v209 offset:36864
	ds_read_b128 v[210:213], v209 offset:37888
	ds_read_b128 v[214:217], v209 offset:38912
	ds_read_b128 v[218:221], v209 offset:39936
	s_nop 0
	global_load_lds_dwordx4 v184, s[22:23]
	v_add_u32_e32 v184, s14, v193
	s_mov_b32 m0, s35
	s_nop 0
	global_load_lds_dwordx4 v184, s[22:23]
	s_waitcnt vmcnt(8)
	s_waitcnt lgkmcnt(0)
	s_barrier
	s_waitcnt lgkmcnt(0)
	v_mfma_f32_16x16x32_bf16 v[120:123], v[128:131], v[164:167], v[120:123]
	v_mfma_f32_16x16x32_bf16 v[56:59], v[136:139], v[164:167], v[56:59]
	v_mfma_f32_16x16x32_bf16 v[112:115], v[128:131], v[172:175], v[112:115]
	v_mfma_f32_16x16x32_bf16 v[48:51], v[136:139], v[172:175], v[48:51]
	v_mfma_f32_16x16x32_bf16 v[104:107], v[128:131], v[180:183], v[104:107]
	v_mfma_f32_16x16x32_bf16 v[40:43], v[136:139], v[180:183], v[40:43]
	v_mfma_f32_16x16x32_bf16 v[96:99], v[128:131], v[214:217], v[96:99]
	v_mfma_f32_16x16x32_bf16 v[32:35], v[136:139], v[214:217], v[32:35]
	v_mfma_f32_16x16x32_bf16 v[120:123], v[132:135], v[168:171], v[120:123]
	v_mfma_f32_16x16x32_bf16 v[56:59], v[140:143], v[168:171], v[56:59]
	v_mfma_f32_16x16x32_bf16 v[112:115], v[132:135], v[176:179], v[112:115]
	v_mfma_f32_16x16x32_bf16 v[48:51], v[140:143], v[176:179], v[48:51]
	v_mfma_f32_16x16x32_bf16 v[104:107], v[132:135], v[210:213], v[104:107]
	v_mfma_f32_16x16x32_bf16 v[40:43], v[140:143], v[210:213], v[40:43]
	v_mfma_f32_16x16x32_bf16 v[96:99], v[132:135], v[218:221], v[96:99]
	v_mfma_f32_16x16x32_bf16 v[32:35], v[140:143], v[218:221], v[32:35]
	v_mfma_f32_16x16x32_bf16 v[124:127], v[144:147], v[164:167], v[124:127]
	v_mfma_f32_16x16x32_bf16 v[60:63], v[152:155], v[164:167], v[60:63]
	v_mfma_f32_16x16x32_bf16 v[116:119], v[144:147], v[172:175], v[116:119]
	v_mfma_f32_16x16x32_bf16 v[52:55], v[152:155], v[172:175], v[52:55]
	v_mfma_f32_16x16x32_bf16 v[108:111], v[144:147], v[180:183], v[108:111]
	v_mfma_f32_16x16x32_bf16 v[44:47], v[152:155], v[180:183], v[44:47]
	v_mfma_f32_16x16x32_bf16 v[100:103], v[144:147], v[214:217], v[100:103]
	v_mfma_f32_16x16x32_bf16 v[36:39], v[152:155], v[214:217], v[36:39]
	v_mfma_f32_16x16x32_bf16 v[124:127], v[148:151], v[168:171], v[124:127]
	v_mfma_f32_16x16x32_bf16 v[60:63], v[156:159], v[168:171], v[60:63]
	v_mfma_f32_16x16x32_bf16 v[116:119], v[148:151], v[176:179], v[116:119]
	v_mfma_f32_16x16x32_bf16 v[52:55], v[156:159], v[176:179], v[52:55]
	v_mfma_f32_16x16x32_bf16 v[108:111], v[148:151], v[210:213], v[108:111]
	v_mfma_f32_16x16x32_bf16 v[44:47], v[156:159], v[210:213], v[44:47]
	v_mfma_f32_16x16x32_bf16 v[100:103], v[148:151], v[218:221], v[100:103]
	v_mfma_f32_16x16x32_bf16 v[36:39], v[156:159], v[218:221], v[36:39]
	s_barrier
	s_or_b32 s14, s13, 0x80
	v_add_u32_e32 v184, s14, v192
	s_add_i32 s15, s15, s26
	ds_read_b128 v[164:167], v209 offset:49152
	ds_read_b128 v[168:171], v209 offset:50176
	ds_read_b128 v[172:175], v209 offset:51200
	ds_read_b128 v[176:179], v209 offset:52224
	ds_read_b128 v[180:183], v209 offset:53248
	ds_read_b128 v[210:213], v209 offset:54272
	ds_read_b128 v[214:217], v209 offset:55296
	ds_read_b128 v[218:221], v209 offset:56320
	s_mov_b32 m0, s15
	s_add_i32 s13, s13, 0x40080
	global_load_lds_dwordx4 v184, s[36:37]
	v_add_u32_e32 v184, s14, v194
	s_add_i32 m0, s15, 0x2000
	s_add_i32 s14, s16, s26
	global_load_lds_dwordx4 v184, s[36:37]
	v_add_u32_e32 v184, s13, v192
	s_mov_b32 m0, s14
	s_nop 0
	global_load_lds_dwordx4 v184, s[36:37]
	v_add_u32_e32 v184, s13, v194
	s_add_i32 m0, s14, 0x2000
	s_nop 0
	global_load_lds_dwordx4 v184, s[36:37]
	v_add_u32_e32 v184, s12, v191
	s_mov_b32 m0, s61
	s_nop 0
	global_load_lds_dwordx4 v184, s[22:23]
	v_add_u32_e32 v184, s12, v193
	s_mov_b32 m0, s63
	s_nop 0
	global_load_lds_dwordx4 v184, s[22:23]
	s_waitcnt vmcnt(8)
	s_waitcnt lgkmcnt(0)
	s_barrier
	s_waitcnt lgkmcnt(0)
	v_mfma_f32_16x16x32_bf16 v[88:91], v[128:131], v[164:167], v[88:91]
	v_mfma_f32_16x16x32_bf16 v[24:27], v[136:139], v[164:167], v[24:27]
	v_mfma_f32_16x16x32_bf16 v[72:75], v[128:131], v[172:175], v[72:75]
	v_mfma_f32_16x16x32_bf16 v[8:11], v[136:139], v[172:175], v[8:11]
	v_mfma_f32_16x16x32_bf16 v[68:71], v[128:131], v[180:183], v[68:71]
	v_mfma_f32_16x16x32_bf16 v[4:7], v[136:139], v[180:183], v[4:7]
	v_mfma_f32_16x16x32_bf16 v[64:67], v[128:131], v[214:217], v[64:67]
	v_mfma_f32_16x16x32_bf16 v[0:3], v[136:139], v[214:217], v[0:3]
	v_mfma_f32_16x16x32_bf16 v[88:91], v[132:135], v[168:171], v[88:91]
	v_mfma_f32_16x16x32_bf16 v[24:27], v[140:143], v[168:171], v[24:27]
	v_mfma_f32_16x16x32_bf16 v[72:75], v[132:135], v[176:179], v[72:75]
	v_mfma_f32_16x16x32_bf16 v[8:11], v[140:143], v[176:179], v[8:11]
	v_mfma_f32_16x16x32_bf16 v[68:71], v[132:135], v[210:213], v[68:71]
	v_mfma_f32_16x16x32_bf16 v[4:7], v[140:143], v[210:213], v[4:7]
	v_mfma_f32_16x16x32_bf16 v[64:67], v[132:135], v[218:221], v[64:67]
	v_mfma_f32_16x16x32_bf16 v[0:3], v[140:143], v[218:221], v[0:3]
	v_mfma_f32_16x16x32_bf16 v[92:95], v[144:147], v[164:167], v[92:95]
	v_mfma_f32_16x16x32_bf16 v[28:31], v[152:155], v[164:167], v[28:31]
	v_mfma_f32_16x16x32_bf16 v[76:79], v[144:147], v[172:175], v[76:79]
	v_mfma_f32_16x16x32_bf16 v[16:19], v[152:155], v[172:175], v[16:19]
	v_mfma_f32_16x16x32_bf16 v[84:87], v[144:147], v[180:183], v[84:87]
	v_mfma_f32_16x16x32_bf16 v[20:23], v[152:155], v[180:183], v[20:23]
	v_mfma_f32_16x16x32_bf16 v[80:83], v[144:147], v[214:217], v[80:83]
	v_mfma_f32_16x16x32_bf16 v[12:15], v[152:155], v[214:217], v[12:15]
	v_mfma_f32_16x16x32_bf16 v[92:95], v[148:151], v[168:171], v[92:95]
	v_mfma_f32_16x16x32_bf16 v[28:31], v[156:159], v[168:171], v[28:31]
	v_mfma_f32_16x16x32_bf16 v[76:79], v[148:151], v[176:179], v[76:79]
	v_mfma_f32_16x16x32_bf16 v[16:19], v[156:159], v[176:179], v[16:19]
	v_mfma_f32_16x16x32_bf16 v[84:87], v[148:151], v[210:213], v[84:87]
	v_mfma_f32_16x16x32_bf16 v[20:23], v[156:159], v[210:213], v[20:23]
	v_mfma_f32_16x16x32_bf16 v[80:83], v[148:151], v[218:221], v[80:83]
	v_mfma_f32_16x16x32_bf16 v[12:15], v[156:159], v[218:221], v[12:15]
	s_barrier
	s_add_i32 s11, s11, 2
	s_addk_i32 s2, 0x100
	s_addk_i32 s3, 0x100
	s_cmp_gt_u32 s11, 13
	s_cbranch_scc1 .Lpeel_done_780
